# same as previous (out-proj deep residual prefetch + graduated waits) with the 12 now-redundant s_nop 0 after the post-store s_nop 1 removed
# baseline (speedup 1.0000x reference)
; __device__ __forceinline__ unsigned cvt_pk_bf16(float lo, float hi) { unsigned r; asm volatile("v_cvt_pk_bf16_f32 %0, %1, %2" : "=v"(r) : "v"(lo), "v"(hi)); return r; }
;     __device__ __forceinline__ void operator()(const f32x4 (&acc)[2][2][4][2], const Unit& u, int wr, int wc, int fr, int fq) const {
;     ...
;         if (F32BASE) {
; #pragma unroll
;             for (int ai = 0; ai < 2; ++ai)
; #pragma unroll
;                 for (int m = 0; m < 4; ++m) { const size_t roff = (size_t)(row0 + ai * HALF + m * 16) * ldc + col0;
; #pragma unroll
;                     for (int bj = 0; bj < 2; ++bj) { const size_t off = roff + bj * HALF; const f32x4 v0 = acc[ai][bj][m][0] + *(const f32x4*)(basef + off), v1 = acc[ai][bj][m][1] + *(const f32x4*)(basef + off + 4);
;                         u32x4 w; w.x = cvt_pk_bf16(v0[0], v0[1]); w.y = cvt_pk_bf16(v0[2], v0[3]); w.z = cvt_pk_bf16(v1[0], v1[1]); w.w = cvt_pk_bf16(v1[2], v1[3]);
;                         *(u32x4*)(outb + off) = w; }
;                     if (m & 1) asm volatile("" ::: "memory"); }
.LBB0_248:
	v_lshl_add_u32 v148, s68, 8, v150
	v_lshl_or_b32 v146, s24, 8, v152
	v_ashrrev_i32_e32 v149, 31, v148
	v_ashrrev_i32_e32 v147, 31, v146
	v_lshlrev_b64 v[144:145], 11, v[148:149]
	v_lshl_add_u64 v[144:145], v[144:145], 0, v[146:147]
	v_lshl_add_u64 v[164:165], v[144:145], 2, s[36:37]
	global_load_dwordx4 v[156:159], v[164:165], off
	global_load_dwordx4 v[160:163], v[164:165], off offset:16
	global_load_dwordx4 v[176:179], v[164:165], off offset:512
	global_load_dwordx4 v[180:183], v[164:165], off offset:528
	v_lshl_add_u64 v[166:167], v[144:145], 1, s[52:53]
	s_mov_b64 s[24:25], 0x40000
	s_andn2_b64 vcc, exec, s[4:5]
	s_mov_b64 s[4:5], -1
	s_waitcnt vmcnt(2)
	v_pk_add_f32 v[124:125], v[124:125], v[156:157]
	v_pk_add_f32 v[156:157], v[122:123], v[162:163]
	v_pk_add_f32 v[122:123], v[120:121], v[160:161]
	v_pk_add_f32 v[126:127], v[126:127], v[158:159]
	v_cvt_pk_bf16_f32 v120, v124, v125
	s_nop 0
	v_cvt_pk_bf16_f32 v121, v126, v127
	v_cvt_pk_bf16_f32 v122, v122, v123
	v_cvt_pk_bf16_f32 v123, v156, v157
	global_store_dwordx4 v[166:167], v[120:123], off
	s_nop 1
	v_or_b32_e32 v156, 16, v148
	v_ashrrev_i32_e32 v157, 31, v156
	v_lshlrev_b64 v[156:157], 11, v[156:157]
	v_lshl_add_u64 v[156:157], v[156:157], 0, v[146:147]
	v_lshl_add_u64 v[158:159], v[156:157], 2, s[36:37]
	global_load_dwordx4 v[184:187], v[158:159], off
	global_load_dwordx4 v[188:191], v[158:159], off offset:16
	global_load_dwordx4 v[192:195], v[158:159], off offset:512
	global_load_dwordx4 v[196:199], v[158:159], off offset:528
	s_waitcnt vmcnt(6)
	v_pk_add_f32 v[116:117], v[116:117], v[176:177]
	s_waitcnt vmcnt(5)
	v_pk_add_f32 v[120:121], v[114:115], v[182:183]
	v_pk_add_f32 v[114:115], v[112:113], v[180:181]
	v_pk_add_f32 v[118:119], v[118:119], v[178:179]
	v_cvt_pk_bf16_f32 v112, v116, v117
	s_nop 0
	v_cvt_pk_bf16_f32 v113, v118, v119
	v_cvt_pk_bf16_f32 v114, v114, v115
	v_cvt_pk_bf16_f32 v115, v120, v121
	global_store_dwordx4 v[166:167], v[112:115], off offset:256
	s_nop 1
	v_lshl_add_u64 v[120:121], v[156:157], 1, s[52:53]
	s_waitcnt vmcnt(4)
	v_pk_add_f32 v[108:109], v[108:109], v[184:185]
	s_waitcnt vmcnt(3)
	v_pk_add_f32 v[112:113], v[106:107], v[190:191]
	v_pk_add_f32 v[106:107], v[104:105], v[188:189]
	v_pk_add_f32 v[110:111], v[110:111], v[186:187]
	v_cvt_pk_bf16_f32 v104, v108, v109
	s_nop 0
	v_cvt_pk_bf16_f32 v105, v110, v111
	v_cvt_pk_bf16_f32 v106, v106, v107
	v_cvt_pk_bf16_f32 v107, v112, v113
	global_store_dwordx4 v[120:121], v[104:107], off
	s_nop 1
	v_or_b32_e32 v112, 32, v148
	v_ashrrev_i32_e32 v113, 31, v112
	v_lshlrev_b64 v[112:113], 11, v[112:113]
	v_lshl_add_u64 v[112:113], v[112:113], 0, v[146:147]
	v_lshl_add_u64 v[114:115], v[112:113], 2, s[36:37]
	global_load_dwordx4 v[168:171], v[114:115], off
	global_load_dwordx4 v[172:175], v[114:115], off offset:16
	global_load_dwordx4 v[176:179], v[114:115], off offset:512
	global_load_dwordx4 v[180:183], v[114:115], off offset:528
	s_waitcnt vmcnt(7)
	v_pk_add_f32 v[100:101], v[100:101], v[192:193]
	s_waitcnt vmcnt(6)
	v_pk_add_f32 v[104:105], v[98:99], v[198:199]
	v_pk_add_f32 v[98:99], v[96:97], v[196:197]
	v_pk_add_f32 v[102:103], v[102:103], v[194:195]
	v_cvt_pk_bf16_f32 v96, v100, v101
	s_nop 0
	v_cvt_pk_bf16_f32 v97, v102, v103
	v_cvt_pk_bf16_f32 v98, v98, v99
	v_cvt_pk_bf16_f32 v99, v104, v105
	global_store_dwordx4 v[120:121], v[96:99], off offset:256
	s_nop 1
	v_lshl_add_u64 v[104:105], v[112:113], 1, s[52:53]
	s_waitcnt vmcnt(4)
	v_pk_add_f32 v[92:93], v[92:93], v[168:169]
	s_waitcnt vmcnt(3)
	v_pk_add_f32 v[96:97], v[90:91], v[174:175]
	v_pk_add_f32 v[90:91], v[88:89], v[172:173]
	v_pk_add_f32 v[94:95], v[94:95], v[170:171]
	v_cvt_pk_bf16_f32 v88, v92, v93
	s_nop 0
	v_cvt_pk_bf16_f32 v89, v94, v95
	v_cvt_pk_bf16_f32 v90, v90, v91
	v_cvt_pk_bf16_f32 v91, v96, v97
	global_store_dwordx4 v[104:105], v[88:91], off
	s_nop 1
	v_or_b32_e32 v96, 48, v148
	v_ashrrev_i32_e32 v97, 31, v96
	v_lshlrev_b64 v[96:97], 11, v[96:97]
	v_lshl_add_u64 v[96:97], v[96:97], 0, v[146:147]
	v_lshl_add_u64 v[98:99], v[96:97], 2, s[36:37]
	global_load_dwordx4 v[184:187], v[98:99], off
	global_load_dwordx4 v[188:191], v[98:99], off offset:16
	global_load_dwordx4 v[192:195], v[98:99], off offset:512
	global_load_dwordx4 v[196:199], v[98:99], off offset:528
	s_waitcnt vmcnt(7)
	v_pk_add_f32 v[84:85], v[84:85], v[176:177]
	s_waitcnt vmcnt(6)
	v_pk_add_f32 v[88:89], v[82:83], v[182:183]
	v_pk_add_f32 v[82:83], v[80:81], v[180:181]
	v_pk_add_f32 v[86:87], v[86:87], v[178:179]
	v_cvt_pk_bf16_f32 v80, v84, v85
	s_nop 0
	v_cvt_pk_bf16_f32 v81, v86, v87
	v_cvt_pk_bf16_f32 v82, v82, v83
	v_cvt_pk_bf16_f32 v83, v88, v89
	global_store_dwordx4 v[104:105], v[80:83], off offset:256
	s_nop 1
	v_lshl_add_u64 v[88:89], v[96:97], 1, s[52:53]
	s_waitcnt vmcnt(4)
	v_pk_add_f32 v[76:77], v[76:77], v[184:185]
	s_waitcnt vmcnt(3)
	v_pk_add_f32 v[80:81], v[74:75], v[190:191]
	v_pk_add_f32 v[74:75], v[72:73], v[188:189]
	v_pk_add_f32 v[78:79], v[78:79], v[186:187]
	v_cvt_pk_bf16_f32 v72, v76, v77
	s_nop 0
	v_cvt_pk_bf16_f32 v73, v78, v79
	v_cvt_pk_bf16_f32 v74, v74, v75
	v_cvt_pk_bf16_f32 v75, v80, v81
	global_store_dwordx4 v[88:89], v[72:75], off
	s_nop 1
	v_lshl_add_u64 v[80:81], v[144:145], 0, s[24:25]
	v_lshl_add_u64 v[82:83], v[80:81], 2, s[36:37]
	s_mov_b64 s[24:25], 0x48000
	global_load_dwordx4 v[168:171], v[82:83], off
	global_load_dwordx4 v[172:175], v[82:83], off offset:16
	global_load_dwordx4 v[176:179], v[82:83], off offset:512
	global_load_dwordx4 v[180:183], v[82:83], off offset:528
	s_waitcnt vmcnt(7)
; __device__ __forceinline__ unsigned cvt_pk_bf16(float lo, float hi) { unsigned r; asm volatile("v_cvt_pk_bf16_f32 %0, %1, %2" : "=v"(r) : "v"(lo), "v"(hi)); return r; }
;     __device__ __forceinline__ void operator()(const f32x4 (&acc)[2][2][4][2], const Unit& u, int wr, int wc, int fr, int fq) const {
;     ...
;         if (F32BASE) {
; #pragma unroll
;             for (int ai = 0; ai < 2; ++ai)
; #pragma unroll
;                 for (int m = 0; m < 4; ++m) { const size_t roff = (size_t)(row0 + ai * HALF + m * 16) * ldc + col0;
; #pragma unroll
;                     for (int bj = 0; bj < 2; ++bj) { const size_t off = roff + bj * HALF; const f32x4 v0 = acc[ai][bj][m][0] + *(const f32x4*)(basef + off), v1 = acc[ai][bj][m][1] + *(const f32x4*)(basef + off + 4);
;                         u32x4 w; w.x = cvt_pk_bf16(v0[0], v0[1]); w.y = cvt_pk_bf16(v0[2], v0[3]); w.z = cvt_pk_bf16(v1[0], v1[1]); w.w = cvt_pk_bf16(v1[2], v1[3]);
;                         *(u32x4*)(outb + off) = w; }
;                     if (m & 1) asm volatile("" ::: "memory"); }
	v_pk_add_f32 v[68:69], v[68:69], v[192:193]
	s_waitcnt vmcnt(6)
	v_pk_add_f32 v[72:73], v[66:67], v[198:199]
	v_pk_add_f32 v[66:67], v[64:65], v[196:197]
	v_pk_add_f32 v[70:71], v[70:71], v[194:195]
	v_cvt_pk_bf16_f32 v64, v68, v69
	s_nop 0
	v_cvt_pk_bf16_f32 v65, v70, v71
	v_cvt_pk_bf16_f32 v66, v66, v67
	v_cvt_pk_bf16_f32 v67, v72, v73
	global_store_dwordx4 v[88:89], v[64:67], off offset:256
	s_nop 1
	v_lshl_add_u64 v[72:73], v[80:81], 1, s[52:53]
	s_waitcnt vmcnt(4)
	v_pk_add_f32 v[60:61], v[60:61], v[168:169]
	s_waitcnt vmcnt(3)
	v_pk_add_f32 v[64:65], v[58:59], v[174:175]
	v_pk_add_f32 v[58:59], v[56:57], v[172:173]
	v_pk_add_f32 v[62:63], v[62:63], v[170:171]
	v_cvt_pk_bf16_f32 v56, v60, v61
	s_nop 0
	v_cvt_pk_bf16_f32 v57, v62, v63
	v_cvt_pk_bf16_f32 v58, v58, v59
	v_cvt_pk_bf16_f32 v59, v64, v65
	global_store_dwordx4 v[72:73], v[56:59], off
	s_nop 1
	v_lshl_add_u64 v[64:65], v[144:145], 0, s[24:25]
	v_lshl_add_u64 v[66:67], v[64:65], 2, s[36:37]
	global_load_dwordx4 v[184:187], v[66:67], off
	global_load_dwordx4 v[188:191], v[66:67], off offset:16
	global_load_dwordx4 v[192:195], v[66:67], off offset:512
	global_load_dwordx4 v[196:199], v[66:67], off offset:528
	s_waitcnt vmcnt(7)
	v_pk_add_f32 v[52:53], v[52:53], v[176:177]
	s_waitcnt vmcnt(6)
	v_pk_add_f32 v[56:57], v[50:51], v[182:183]
	v_pk_add_f32 v[50:51], v[48:49], v[180:181]
	v_pk_add_f32 v[54:55], v[54:55], v[178:179]
	v_cvt_pk_bf16_f32 v48, v52, v53
	s_nop 0
	v_cvt_pk_bf16_f32 v49, v54, v55
	v_cvt_pk_bf16_f32 v50, v50, v51
	v_cvt_pk_bf16_f32 v51, v56, v57
	global_store_dwordx4 v[72:73], v[48:51], off offset:256
	s_nop 1
	v_lshl_add_u64 v[56:57], v[64:65], 1, s[52:53]
	s_waitcnt vmcnt(4)
	v_pk_add_f32 v[44:45], v[44:45], v[184:185]
	s_waitcnt vmcnt(3)
	v_pk_add_f32 v[48:49], v[42:43], v[190:191]
	v_pk_add_f32 v[42:43], v[40:41], v[188:189]
	v_pk_add_f32 v[46:47], v[46:47], v[186:187]
	v_cvt_pk_bf16_f32 v40, v44, v45
	s_nop 0
	v_cvt_pk_bf16_f32 v41, v46, v47
	v_cvt_pk_bf16_f32 v42, v42, v43
	v_cvt_pk_bf16_f32 v43, v48, v49
	global_store_dwordx4 v[56:57], v[40:43], off
	s_nop 1
	v_lshl_add_u64 v[48:49], v[144:145], 0, s[44:45]
	v_lshl_add_u64 v[50:51], v[48:49], 2, s[36:37]
	global_load_dwordx4 v[168:171], v[50:51], off
	global_load_dwordx4 v[172:175], v[50:51], off offset:16
	global_load_dwordx4 v[176:179], v[50:51], off offset:512
	global_load_dwordx4 v[180:183], v[50:51], off offset:528
	s_waitcnt vmcnt(7)
	v_pk_add_f32 v[36:37], v[36:37], v[192:193]
	s_waitcnt vmcnt(6)
	v_pk_add_f32 v[40:41], v[34:35], v[198:199]
	v_pk_add_f32 v[34:35], v[32:33], v[196:197]
	v_pk_add_f32 v[38:39], v[38:39], v[194:195]
	v_cvt_pk_bf16_f32 v32, v36, v37
	s_nop 0
	v_cvt_pk_bf16_f32 v33, v38, v39
	v_cvt_pk_bf16_f32 v34, v34, v35
	v_cvt_pk_bf16_f32 v35, v40, v41
	global_store_dwordx4 v[56:57], v[32:35], off offset:256
	s_nop 1
	v_lshl_add_u64 v[40:41], v[48:49], 1, s[52:53]
	s_waitcnt vmcnt(4)
	v_pk_add_f32 v[28:29], v[28:29], v[168:169]
	s_waitcnt vmcnt(3)
	v_pk_add_f32 v[32:33], v[26:27], v[174:175]
	v_pk_add_f32 v[26:27], v[24:25], v[172:173]
	v_pk_add_f32 v[30:31], v[30:31], v[170:171]
	v_cvt_pk_bf16_f32 v24, v28, v29
	s_nop 0
	v_cvt_pk_bf16_f32 v25, v30, v31
	v_cvt_pk_bf16_f32 v26, v26, v27
	v_cvt_pk_bf16_f32 v27, v32, v33
	global_store_dwordx4 v[40:41], v[24:27], off
	s_nop 1
	v_lshl_add_u64 v[32:33], v[144:145], 0, s[48:49]
	v_lshl_add_u64 v[34:35], v[32:33], 2, s[36:37]
	global_load_dwordx4 v[184:187], v[34:35], off
	global_load_dwordx4 v[188:191], v[34:35], off offset:16
	global_load_dwordx4 v[192:195], v[34:35], off offset:512
	global_load_dwordx4 v[196:199], v[34:35], off offset:528
	s_waitcnt vmcnt(7)
	v_pk_add_f32 v[20:21], v[20:21], v[176:177]
	s_waitcnt vmcnt(6)
	v_pk_add_f32 v[24:25], v[18:19], v[182:183]
	v_pk_add_f32 v[18:19], v[16:17], v[180:181]
	v_pk_add_f32 v[22:23], v[22:23], v[178:179]
	v_cvt_pk_bf16_f32 v16, v20, v21
	s_nop 0
	v_cvt_pk_bf16_f32 v17, v22, v23
	v_cvt_pk_bf16_f32 v18, v18, v19
	v_cvt_pk_bf16_f32 v19, v24, v25
	global_store_dwordx4 v[40:41], v[16:19], off offset:256
	s_nop 1
	v_lshl_add_u64 v[24:25], v[32:33], 1, s[52:53]
	s_waitcnt vmcnt(4)
	v_pk_add_f32 v[12:13], v[12:13], v[184:185]
	s_waitcnt vmcnt(3)
	v_pk_add_f32 v[16:17], v[10:11], v[190:191]
	v_pk_add_f32 v[10:11], v[8:9], v[188:189]
	v_pk_add_f32 v[14:15], v[14:15], v[186:187]
	v_cvt_pk_bf16_f32 v8, v12, v13
	s_nop 0
	v_cvt_pk_bf16_f32 v9, v14, v15
	v_cvt_pk_bf16_f32 v10, v10, v11
	v_cvt_pk_bf16_f32 v11, v16, v17
	global_store_dwordx4 v[24:25], v[8:11], off
	s_nop 1
	s_waitcnt vmcnt(3)
	v_pk_add_f32 v[4:5], v[4:5], v[192:193]
	s_waitcnt vmcnt(2)
	v_pk_add_f32 v[8:9], v[2:3], v[198:199]
	v_pk_add_f32 v[2:3], v[0:1], v[196:197]
	v_pk_add_f32 v[6:7], v[6:7], v[194:195]
	v_cvt_pk_bf16_f32 v0, v4, v5
	s_nop 0
	v_cvt_pk_bf16_f32 v1, v6, v7
	v_cvt_pk_bf16_f32 v2, v2, v3
	v_cvt_pk_bf16_f32 v3, v8, v9
	global_store_dwordx4 v[24:25], v[0:3], off offset:256
	s_cbranch_vccnz .LBB0_237
	s_andn2_b64 vcc, exec, s[6:7]
	s_cbranch_vccnz .LBB0_236
	s_barrier
	s_branch .LBB0_236
